# v077 + GU accumulator re-zeroing folded into the epilogue (each accumulator pair cleared right after its last use) instead of a 64-instruction block in the tile-loop header
# speedup vs baseline: 1.0121x; 1.0121x over previous
.LBB0_1428:
	s_add_u32 s8, s22, 0x4000
	s_addc_u32 s9, s23, 0
	s_add_u32 s10, s22, 0x5858000
	s_addc_u32 s11, s23, 0
	s_lshl_b32 s5, s12, 5
	s_and_b32 s61, s5, 0x60
	s_add_i32 m0, s56, 0x18000
	v_lshl_add_u64 v[6:7], v[6:7], 0, s[40:41]
	s_lshl_b32 s60, s3, 6
	s_lshl_b32 s3, s3, 13
	s_lshl_b32 s16, s61, 7
	s_waitcnt vmcnt(4)
	s_barrier
	global_load_lds_dwordx4 v[6:7], off
	v_lshl_add_u64 v[4:5], v[4:5], 0, s[40:41]
	s_add_i32 m0, s56, 0x1a000
	s_add_i32 s62, s56, 0x8000
	s_add_i32 s63, s56, 0xa000
	global_load_lds_dwordx4 v[4:5], off
	v_lshl_add_u64 v[2:3], v[2:3], 0, s[40:41]
	s_mov_b32 m0, s62
	s_add_u32 s12, s50, 0x40080
	global_load_lds_dwordx4 v[2:3], off
	v_lshl_add_u64 v[0:1], v[0:1], 0, s[40:41]
	s_mov_b32 m0, s63
	s_addc_u32 s13, s51, 0
	global_load_lds_dwordx4 v[0:1], off
	s_add_i32 m0, s56, 0x1c000
	v_lshl_add_u64 v[0:1], s[12:13], 0, v[176:177]
	global_load_lds_dwordx4 v[0:1], off
	v_lshl_add_u64 v[0:1], s[12:13], 0, v[160:161]
	s_add_i32 m0, s56, 0x1e000
	v_bfe_u32 v199, v231, 4, 2
	global_load_lds_dwordx4 v[0:1], off
	v_and_b32_e32 v198, 15, v231
	v_lshlrev_b32_e32 v0, 4, v199
	v_lshlrev_b32_e32 v1, 2, v231
	v_lshl_or_b32 v0, v198, 6, v0
	v_and_b32_e32 v1, 32, v1
	v_bitop3_b32 v2, v0, s3, v1 bitop3:0xde
	v_bitop3_b32 v200, s16, v0, v1 bitop3:0xf6
	v_lshlrev_b32_e32 v0, 14, v8
	v_and_b32_e32 v0, 0xffff8000, v0
	v_lshl_add_u32 v0, v9, 11, v0
	v_and_b32_e32 v1, 1, v8
	v_lshl_or_b32 v0, v1, 6, v0
	v_lshl_add_u32 v162, v10, 1, v0
	v_lshlrev_b32_e32 v0, 14, v11
	v_and_b32_e32 v0, 0xffff8000, v0
	s_waitcnt vmcnt(6)
	v_lshl_add_u32 v0, v12, 11, v0
	v_and_b32_e32 v1, 1, v11
	v_lshl_or_b32 v0, v1, 6, v0
	s_sext_i32_i16 s5, s2
	s_ashr_i32 s64, s94, 31
	v_mov_b32_e32 v163, v177
	v_lshl_add_u32 v164, v13, 1, v0
	v_mov_b32_e32 v165, v177
	s_mov_b32 s65, 0
	v_add_u32_e32 v201, 0, v2
	s_barrier
	v_mov_b64_e32 v[6:7], 0
	v_mov_b64_e32 v[8:9], 0
	v_mov_b64_e32 v[10:11], 0
	v_mov_b64_e32 v[12:13], 0
	v_mov_b64_e32 v[14:15], 0
	v_mov_b64_e32 v[16:17], 0
	v_mov_b64_e32 v[18:19], 0
	v_mov_b64_e32 v[20:21], 0
	v_mov_b64_e32 v[22:23], 0
	v_mov_b64_e32 v[24:25], 0
	v_mov_b64_e32 v[26:27], 0
	v_mov_b64_e32 v[28:29], 0
	v_mov_b64_e32 v[30:31], 0
	v_mov_b64_e32 v[32:33], 0
	v_mov_b64_e32 v[34:35], 0
	v_mov_b64_e32 v[36:37], 0
	v_mov_b64_e32 v[38:39], 0
	v_mov_b64_e32 v[40:41], 0
	v_mov_b64_e32 v[42:43], 0
	v_mov_b64_e32 v[44:45], 0
	v_mov_b64_e32 v[46:47], 0
	v_mov_b64_e32 v[48:49], 0
	v_mov_b64_e32 v[50:51], 0
	v_mov_b64_e32 v[52:53], 0
	v_mov_b64_e32 v[54:55], 0
	v_mov_b64_e32 v[56:57], 0
	v_mov_b64_e32 v[58:59], 0
	v_mov_b64_e32 v[60:61], 0
	v_mov_b64_e32 v[62:63], 0
	v_mov_b64_e32 v[64:65], 0
	v_mov_b64_e32 v[66:67], 0
	v_mov_b64_e32 v[68:69], 0
	v_mov_b64_e32 v[70:71], 0
	v_mov_b64_e32 v[72:73], 0
	v_mov_b64_e32 v[74:75], 0
	v_mov_b64_e32 v[76:77], 0
	v_mov_b64_e32 v[78:79], 0
	v_mov_b64_e32 v[80:81], 0
	v_mov_b64_e32 v[82:83], 0
	v_mov_b64_e32 v[84:85], 0
	v_mov_b64_e32 v[86:87], 0
	v_mov_b64_e32 v[88:89], 0
	v_mov_b64_e32 v[90:91], 0
	v_mov_b64_e32 v[92:93], 0
	v_mov_b64_e32 v[94:95], 0
	v_mov_b64_e32 v[96:97], 0
	v_mov_b64_e32 v[98:99], 0
	v_mov_b64_e32 v[100:101], 0
	v_mov_b64_e32 v[102:103], 0
	v_mov_b64_e32 v[104:105], 0
	v_mov_b64_e32 v[106:107], 0
	v_mov_b64_e32 v[108:109], 0
	v_mov_b64_e32 v[110:111], 0
	v_mov_b64_e32 v[112:113], 0
	v_mov_b64_e32 v[114:115], 0
	v_mov_b64_e32 v[116:117], 0
	v_mov_b64_e32 v[118:119], 0
	v_mov_b64_e32 v[120:121], 0
	v_mov_b64_e32 v[122:123], 0
	v_mov_b64_e32 v[124:125], 0
	v_mov_b64_e32 v[126:127], 0

.LBB0_1435:
	s_ashr_i32 s17, s16, 31
	v_cmp_lt_i64_e32 vcc, s[18:19], v[186:187]
	s_lshl_b64 s[18:19], s[16:17], 19
	s_add_u32 s18, s47, s18
	s_addc_u32 s19, s54, s19
	s_and_b64 s[20:21], vcc, exec
	s_cselect_b32 s17, s19, s7
	s_cselect_b32 s66, s18, s6
	s_ashr_i32 s13, s12, 31
	s_lshl_b64 s[20:21], s[12:13], 19
	s_add_u32 s20, s37, s20
	s_addc_u32 s21, s46, s21
	s_and_b64 s[52:53], vcc, exec
	s_cselect_b32 s13, s21, s51
	s_cselect_b32 s67, s20, s50
	s_add_u32 s6, s6, 0x40080
	s_addc_u32 s7, s7, 0
	s_add_u32 s68, s50, 0x100
	v_mov_b64_e32 v[0:1], 0
	v_mov_b64_e32 v[2:3], 0
	v_mov_b64_e32 v[4:5], 0
	s_addc_u32 s69, s51, 0
	s_mov_b32 s70, -2
	v_add_u32_e32 v174, 0x10000, v200
	.p2alignl 6, 3212836864
.LBB0_1436:
	s_add_u32 s28, s6, 0xfffc0080
	s_addc_u32 s29, s7, -1
	s_add_i32 s71, 0, 0x10000
	ds_read_b128 v[128:131], v174
	ds_read_b128 v[132:135], v174 offset:1024
	ds_read_b128 v[136:139], v174 offset:2048
	ds_read_b128 v[140:143], v174 offset:3072
	s_cmp_eq_u32 s70, 12
	s_cselect_b32 s53, s17, s29
	s_cselect_b32 s52, s66, s28
	s_cselect_b32 s51, s13, s69
	s_cselect_b32 s50, s67, s68
	s_add_i32 m0, s56, 0xc000
	ds_read_b128 v[144:147], v201
	ds_read_b128 v[152:155], v201 offset:2048
	ds_read_b128 v[170:173], v201 offset:4096
	ds_read_b128 v[192:195], v201 offset:6144
	ds_read_b128 v[148:151], v201 offset:1024
	ds_read_b128 v[166:169], v201 offset:3072
	ds_read_b128 v[188:191], v201 offset:5120
	ds_read_b128 v[202:205], v201 offset:7168
	global_load_lds_dwordx4 v162, s[6:7]
	s_add_i32 m0, s56, 0xe000
	s_nop 0
	global_load_lds_dwordx4 v164, s[6:7]
	s_waitcnt lgkmcnt(8)
	s_barrier
	s_waitcnt lgkmcnt(7)
	v_mfma_f32_16x16x32_bf16 v[124:127], v[128:131], v[144:147], v[124:127]
	v_mfma_f32_16x16x32_bf16 v[116:119], v[136:139], v[144:147], v[116:119]
	s_waitcnt lgkmcnt(6)
	v_mfma_f32_16x16x32_bf16 v[108:111], v[128:131], v[152:155], v[108:111]
	v_mfma_f32_16x16x32_bf16 v[100:103], v[136:139], v[152:155], v[100:103]
	s_waitcnt lgkmcnt(5)
	v_mfma_f32_16x16x32_bf16 v[92:95], v[128:131], v[170:173], v[92:95]
	v_mfma_f32_16x16x32_bf16 v[84:87], v[136:139], v[170:173], v[84:87]
	s_waitcnt lgkmcnt(4)
	v_mfma_f32_16x16x32_bf16 v[76:79], v[128:131], v[192:195], v[76:79]
	v_mfma_f32_16x16x32_bf16 v[68:71], v[136:139], v[192:195], v[68:71]
	s_waitcnt lgkmcnt(3)
	v_mfma_f32_16x16x32_bf16 v[124:127], v[132:135], v[148:151], v[124:127]
	v_mfma_f32_16x16x32_bf16 v[116:119], v[140:143], v[148:151], v[116:119]
	s_waitcnt lgkmcnt(2)
	v_mfma_f32_16x16x32_bf16 v[108:111], v[132:135], v[166:169], v[108:111]
	v_mfma_f32_16x16x32_bf16 v[100:103], v[140:143], v[166:169], v[100:103]
	s_waitcnt lgkmcnt(1)
	v_mfma_f32_16x16x32_bf16 v[92:95], v[132:135], v[188:191], v[92:95]
	v_mfma_f32_16x16x32_bf16 v[84:87], v[140:143], v[188:191], v[84:87]
	s_waitcnt lgkmcnt(0)
	v_mfma_f32_16x16x32_bf16 v[76:79], v[132:135], v[202:205], v[76:79]
	v_mfma_f32_16x16x32_bf16 v[68:71], v[140:143], v[202:205], v[68:71]
	s_barrier
	s_add_i32 s28, 0, 0x14000
	s_add_i32 s29, s71, s55
	ds_read_b128 v[206:209], v174 offset:16384
	ds_read_b128 v[210:213], v174 offset:17408
	ds_read_b128 v[214:217], v174 offset:18432
	ds_read_b128 v[232:235], v174 offset:19456
	s_mov_b32 m0, s29
	s_nop 0
	global_load_lds_dwordx4 v176, s[50:51]
	s_add_i32 m0, s29, 0x2000
	s_nop 0
	global_load_lds_dwordx4 v160, s[50:51]
	s_barrier
	s_waitcnt lgkmcnt(3)
	v_mfma_f32_16x16x32_bf16 v[120:123], v[206:209], v[144:147], v[120:123]
	s_waitcnt lgkmcnt(1)
	v_mfma_f32_16x16x32_bf16 v[112:115], v[214:217], v[144:147], v[112:115]
	v_mfma_f32_16x16x32_bf16 v[104:107], v[206:209], v[152:155], v[104:107]
	v_mfma_f32_16x16x32_bf16 v[96:99], v[214:217], v[152:155], v[96:99]
	v_mfma_f32_16x16x32_bf16 v[88:91], v[206:209], v[170:173], v[88:91]
	v_mfma_f32_16x16x32_bf16 v[80:83], v[214:217], v[170:173], v[80:83]
	v_mfma_f32_16x16x32_bf16 v[72:75], v[206:209], v[192:195], v[72:75]
	v_mfma_f32_16x16x32_bf16 v[64:67], v[214:217], v[192:195], v[64:67]
	v_mfma_f32_16x16x32_bf16 v[120:123], v[210:213], v[148:151], v[120:123]
	s_waitcnt lgkmcnt(0)
	v_mfma_f32_16x16x32_bf16 v[112:115], v[232:235], v[148:151], v[112:115]
	v_mfma_f32_16x16x32_bf16 v[104:107], v[210:213], v[166:169], v[104:107]
	v_mfma_f32_16x16x32_bf16 v[96:99], v[232:235], v[166:169], v[96:99]
	v_mfma_f32_16x16x32_bf16 v[88:91], v[210:213], v[188:191], v[88:91]
	v_mfma_f32_16x16x32_bf16 v[80:83], v[232:235], v[188:191], v[80:83]
	v_mfma_f32_16x16x32_bf16 v[72:75], v[210:213], v[202:205], v[72:75]
	v_mfma_f32_16x16x32_bf16 v[64:67], v[232:235], v[202:205], v[64:67]
	s_mov_b32 m0, s56
	s_barrier
	ds_read_b128 v[144:147], v201 offset:16384
	ds_read_b128 v[152:155], v201 offset:18432
	ds_read_b128 v[170:173], v201 offset:20480
	ds_read_b128 v[192:195], v201 offset:22528
	ds_read_b128 v[148:151], v201 offset:17408
	ds_read_b128 v[166:169], v201 offset:19456
	ds_read_b128 v[188:191], v201 offset:21504
	ds_read_b128 v[202:205], v201 offset:23552
	global_load_lds_dwordx4 v156, s[52:53]
	s_mov_b32 m0, s57
	s_nop 0
	global_load_lds_dwordx4 v158, s[52:53]
	s_barrier
	s_waitcnt lgkmcnt(7)
	v_mfma_f32_16x16x32_bf16 v[60:63], v[128:131], v[144:147], v[60:63]
	v_mfma_f32_16x16x32_bf16 v[52:55], v[136:139], v[144:147], v[52:55]
	s_waitcnt lgkmcnt(6)
	v_mfma_f32_16x16x32_bf16 v[44:47], v[128:131], v[152:155], v[44:47]
	v_mfma_f32_16x16x32_bf16 v[36:39], v[136:139], v[152:155], v[36:39]
	s_waitcnt lgkmcnt(5)
	v_mfma_f32_16x16x32_bf16 v[28:31], v[128:131], v[170:173], v[28:31]
	v_mfma_f32_16x16x32_bf16 v[20:23], v[136:139], v[170:173], v[20:23]
	s_waitcnt lgkmcnt(4)
	v_mfma_f32_16x16x32_bf16 v[12:15], v[128:131], v[192:195], v[12:15]
	v_mfma_f32_16x16x32_bf16 v[4:7], v[136:139], v[192:195], v[4:7]
	s_waitcnt lgkmcnt(3)
	v_mfma_f32_16x16x32_bf16 v[60:63], v[132:135], v[148:151], v[60:63]
	v_mfma_f32_16x16x32_bf16 v[52:55], v[140:143], v[148:151], v[52:55]
	s_waitcnt lgkmcnt(2)
	v_mfma_f32_16x16x32_bf16 v[44:47], v[132:135], v[166:169], v[44:47]
	v_mfma_f32_16x16x32_bf16 v[36:39], v[140:143], v[166:169], v[36:39]
	s_waitcnt lgkmcnt(1)
	v_mfma_f32_16x16x32_bf16 v[28:31], v[132:135], v[188:191], v[28:31]
	v_mfma_f32_16x16x32_bf16 v[20:23], v[140:143], v[188:191], v[20:23]
	s_waitcnt lgkmcnt(0)
	v_mfma_f32_16x16x32_bf16 v[12:15], v[132:135], v[202:205], v[12:15]
	v_mfma_f32_16x16x32_bf16 v[4:7], v[140:143], v[202:205], v[4:7]
	s_barrier
	s_add_u32 s72, s50, 0x40000
	s_addc_u32 s73, s51, 0
	s_add_i32 s28, s28, s55
	s_mov_b32 m0, s28
	s_nop 0
	global_load_lds_dwordx4 v176, s[72:73]
	s_add_i32 m0, s28, 0x2000
	s_nop 0
	global_load_lds_dwordx4 v160, s[72:73]
	s_waitcnt vmcnt(6)
	s_barrier
	v_mfma_f32_16x16x32_bf16 v[56:59], v[206:209], v[144:147], v[56:59]
	v_mfma_f32_16x16x32_bf16 v[48:51], v[214:217], v[144:147], v[48:51]
	v_mfma_f32_16x16x32_bf16 v[40:43], v[206:209], v[152:155], v[40:43]
	v_mfma_f32_16x16x32_bf16 v[32:35], v[214:217], v[152:155], v[32:35]
	v_mfma_f32_16x16x32_bf16 v[24:27], v[206:209], v[170:173], v[24:27]
	v_mfma_f32_16x16x32_bf16 v[16:19], v[214:217], v[170:173], v[16:19]
	v_mfma_f32_16x16x32_bf16 v[8:11], v[206:209], v[192:195], v[8:11]
	v_mfma_f32_16x16x32_bf16 v[0:3], v[214:217], v[192:195], v[0:3]
	v_mfma_f32_16x16x32_bf16 v[56:59], v[210:213], v[148:151], v[56:59]
	v_mfma_f32_16x16x32_bf16 v[48:51], v[232:235], v[148:151], v[48:51]
	v_mfma_f32_16x16x32_bf16 v[40:43], v[210:213], v[166:169], v[40:43]
	v_mfma_f32_16x16x32_bf16 v[32:35], v[232:235], v[166:169], v[32:35]
	v_mfma_f32_16x16x32_bf16 v[24:27], v[210:213], v[188:191], v[24:27]
	v_mfma_f32_16x16x32_bf16 v[16:19], v[232:235], v[188:191], v[16:19]
	v_mfma_f32_16x16x32_bf16 v[8:11], v[210:213], v[202:205], v[8:11]
	v_mfma_f32_16x16x32_bf16 v[0:3], v[232:235], v[202:205], v[0:3]
	s_add_i32 s28, 0, 0x18000
	s_barrier
	ds_read_b128 v[128:131], v174 offset:32768
	ds_read_b128 v[132:135], v174 offset:33792
	ds_read_b128 v[136:139], v174 offset:34816
	ds_read_b128 v[140:143], v174 offset:35840
	s_add_u32 s98, s52, 0x40000
	s_addc_u32 s99, s53, 0
	s_mov_b32 m0, s58
	ds_read_b128 v[144:147], v201 offset:32768
	ds_read_b128 v[152:155], v201 offset:34816
	ds_read_b128 v[170:173], v201 offset:36864
	ds_read_b128 v[192:195], v201 offset:38912
	ds_read_b128 v[148:151], v201 offset:33792
	ds_read_b128 v[166:169], v201 offset:35840
	ds_read_b128 v[188:191], v201 offset:37888
	ds_read_b128 v[202:205], v201 offset:39936
	global_load_lds_dwordx4 v156, s[98:99]
	s_mov_b32 m0, s59
	s_nop 0
	global_load_lds_dwordx4 v158, s[98:99]
	s_waitcnt lgkmcnt(8)
	s_barrier
	s_waitcnt lgkmcnt(7)
	v_mfma_f32_16x16x32_bf16 v[124:127], v[128:131], v[144:147], v[124:127]
	v_mfma_f32_16x16x32_bf16 v[116:119], v[136:139], v[144:147], v[116:119]
	s_waitcnt lgkmcnt(6)
	v_mfma_f32_16x16x32_bf16 v[108:111], v[128:131], v[152:155], v[108:111]
	v_mfma_f32_16x16x32_bf16 v[100:103], v[136:139], v[152:155], v[100:103]
	s_waitcnt lgkmcnt(5)
	v_mfma_f32_16x16x32_bf16 v[92:95], v[128:131], v[170:173], v[92:95]
	v_mfma_f32_16x16x32_bf16 v[84:87], v[136:139], v[170:173], v[84:87]
	s_waitcnt lgkmcnt(4)
	v_mfma_f32_16x16x32_bf16 v[76:79], v[128:131], v[192:195], v[76:79]
	v_mfma_f32_16x16x32_bf16 v[68:71], v[136:139], v[192:195], v[68:71]
	s_waitcnt lgkmcnt(3)
	v_mfma_f32_16x16x32_bf16 v[124:127], v[132:135], v[148:151], v[124:127]
	v_mfma_f32_16x16x32_bf16 v[116:119], v[140:143], v[148:151], v[116:119]
	s_waitcnt lgkmcnt(2)
	v_mfma_f32_16x16x32_bf16 v[108:111], v[132:135], v[166:169], v[108:111]
	v_mfma_f32_16x16x32_bf16 v[100:103], v[140:143], v[166:169], v[100:103]
	s_waitcnt lgkmcnt(1)
	v_mfma_f32_16x16x32_bf16 v[92:95], v[132:135], v[188:191], v[92:95]
	v_mfma_f32_16x16x32_bf16 v[84:87], v[140:143], v[188:191], v[84:87]
	s_waitcnt lgkmcnt(0)
	v_mfma_f32_16x16x32_bf16 v[76:79], v[132:135], v[202:205], v[76:79]
	v_mfma_f32_16x16x32_bf16 v[68:71], v[140:143], v[202:205], v[68:71]
	s_barrier
	s_add_i32 s29, 0, 0x1c000
	s_add_i32 s28, s28, s55
	s_add_i32 m0, s28, 0xffffff80
	ds_read_b128 v[206:209], v174 offset:49152
	ds_read_b128 v[210:213], v174 offset:50176
	ds_read_b128 v[214:217], v174 offset:51200
	ds_read_b128 v[232:235], v174 offset:52224
	global_load_lds_dwordx4 v176, s[50:51] offset:128
	s_add_i32 m0, s28, 0x1f80
	s_nop 0
	global_load_lds_dwordx4 v160, s[50:51] offset:128
	s_barrier
	s_waitcnt lgkmcnt(3)
	v_mfma_f32_16x16x32_bf16 v[120:123], v[206:209], v[144:147], v[120:123]
	s_waitcnt lgkmcnt(1)
	v_mfma_f32_16x16x32_bf16 v[112:115], v[214:217], v[144:147], v[112:115]
	v_mfma_f32_16x16x32_bf16 v[104:107], v[206:209], v[152:155], v[104:107]
	v_mfma_f32_16x16x32_bf16 v[96:99], v[214:217], v[152:155], v[96:99]
	v_mfma_f32_16x16x32_bf16 v[88:91], v[206:209], v[170:173], v[88:91]
	v_mfma_f32_16x16x32_bf16 v[80:83], v[214:217], v[170:173], v[80:83]
	v_mfma_f32_16x16x32_bf16 v[72:75], v[206:209], v[192:195], v[72:75]
	v_mfma_f32_16x16x32_bf16 v[64:67], v[214:217], v[192:195], v[64:67]
	v_mfma_f32_16x16x32_bf16 v[120:123], v[210:213], v[148:151], v[120:123]
	s_waitcnt lgkmcnt(0)
	v_mfma_f32_16x16x32_bf16 v[112:115], v[232:235], v[148:151], v[112:115]
	v_mfma_f32_16x16x32_bf16 v[104:107], v[210:213], v[166:169], v[104:107]
	v_mfma_f32_16x16x32_bf16 v[96:99], v[232:235], v[166:169], v[96:99]
	v_mfma_f32_16x16x32_bf16 v[88:91], v[210:213], v[188:191], v[88:91]
	v_mfma_f32_16x16x32_bf16 v[80:83], v[232:235], v[188:191], v[80:83]
	v_mfma_f32_16x16x32_bf16 v[72:75], v[210:213], v[202:205], v[72:75]
	v_mfma_f32_16x16x32_bf16 v[64:67], v[232:235], v[202:205], v[64:67]
	s_add_i32 m0, s62, 0xffffff80
	s_barrier
	ds_read_b128 v[144:147], v201 offset:49152
	ds_read_b128 v[152:155], v201 offset:51200
	ds_read_b128 v[170:173], v201 offset:53248
	ds_read_b128 v[192:195], v201 offset:55296
	ds_read_b128 v[148:151], v201 offset:50176
	ds_read_b128 v[166:169], v201 offset:52224
	ds_read_b128 v[188:191], v201 offset:54272
	ds_read_b128 v[202:205], v201 offset:56320
	global_load_lds_dwordx4 v156, s[52:53] offset:128
	s_add_i32 m0, s63, 0xffffff80
	s_nop 0
	global_load_lds_dwordx4 v158, s[52:53] offset:128
	s_barrier
	s_waitcnt lgkmcnt(7)
	v_mfma_f32_16x16x32_bf16 v[60:63], v[128:131], v[144:147], v[60:63]
	v_mfma_f32_16x16x32_bf16 v[52:55], v[136:139], v[144:147], v[52:55]
	s_waitcnt lgkmcnt(6)
	v_mfma_f32_16x16x32_bf16 v[44:47], v[128:131], v[152:155], v[44:47]
	v_mfma_f32_16x16x32_bf16 v[36:39], v[136:139], v[152:155], v[36:39]
	s_waitcnt lgkmcnt(5)
	v_mfma_f32_16x16x32_bf16 v[28:31], v[128:131], v[170:173], v[28:31]
	v_mfma_f32_16x16x32_bf16 v[20:23], v[136:139], v[170:173], v[20:23]
	s_waitcnt lgkmcnt(4)
	v_mfma_f32_16x16x32_bf16 v[12:15], v[128:131], v[192:195], v[12:15]
	v_mfma_f32_16x16x32_bf16 v[4:7], v[136:139], v[192:195], v[4:7]
	s_waitcnt lgkmcnt(3)
	v_mfma_f32_16x16x32_bf16 v[60:63], v[132:135], v[148:151], v[60:63]
	v_mfma_f32_16x16x32_bf16 v[52:55], v[140:143], v[148:151], v[52:55]
	s_waitcnt lgkmcnt(2)
	v_mfma_f32_16x16x32_bf16 v[44:47], v[132:135], v[166:169], v[44:47]
	v_mfma_f32_16x16x32_bf16 v[36:39], v[140:143], v[166:169], v[36:39]
	s_waitcnt lgkmcnt(1)
	v_mfma_f32_16x16x32_bf16 v[28:31], v[132:135], v[188:191], v[28:31]
	v_mfma_f32_16x16x32_bf16 v[20:23], v[140:143], v[188:191], v[20:23]
	s_waitcnt lgkmcnt(0)
	v_mfma_f32_16x16x32_bf16 v[12:15], v[132:135], v[202:205], v[12:15]
	v_mfma_f32_16x16x32_bf16 v[4:7], v[140:143], v[202:205], v[4:7]
	s_barrier
	s_add_u32 s50, s50, 0x40080
	s_addc_u32 s51, s51, 0
	s_add_i32 s28, s29, s55
	s_mov_b32 m0, s28
	s_nop 0
	global_load_lds_dwordx4 v176, s[50:51]
	s_add_i32 m0, s28, 0x2000
	s_nop 0
	global_load_lds_dwordx4 v160, s[50:51]
	s_waitcnt vmcnt(6)
	s_barrier
	v_mfma_f32_16x16x32_bf16 v[56:59], v[206:209], v[144:147], v[56:59]
	v_mfma_f32_16x16x32_bf16 v[48:51], v[214:217], v[144:147], v[48:51]
	v_mfma_f32_16x16x32_bf16 v[40:43], v[206:209], v[152:155], v[40:43]
	v_mfma_f32_16x16x32_bf16 v[32:35], v[214:217], v[152:155], v[32:35]
	v_mfma_f32_16x16x32_bf16 v[24:27], v[206:209], v[170:173], v[24:27]
	v_mfma_f32_16x16x32_bf16 v[16:19], v[214:217], v[170:173], v[16:19]
	v_mfma_f32_16x16x32_bf16 v[8:11], v[206:209], v[192:195], v[8:11]
	v_mfma_f32_16x16x32_bf16 v[0:3], v[214:217], v[192:195], v[0:3]
	v_mfma_f32_16x16x32_bf16 v[56:59], v[210:213], v[148:151], v[56:59]
	v_mfma_f32_16x16x32_bf16 v[48:51], v[232:235], v[148:151], v[48:51]
	v_mfma_f32_16x16x32_bf16 v[40:43], v[210:213], v[166:169], v[40:43]
	v_mfma_f32_16x16x32_bf16 v[32:35], v[232:235], v[166:169], v[32:35]
	v_mfma_f32_16x16x32_bf16 v[24:27], v[210:213], v[188:191], v[24:27]
	v_mfma_f32_16x16x32_bf16 v[16:19], v[232:235], v[188:191], v[16:19]
	v_mfma_f32_16x16x32_bf16 v[8:11], v[210:213], v[202:205], v[8:11]
	v_mfma_f32_16x16x32_bf16 v[0:3], v[232:235], v[202:205], v[0:3]
	s_add_i32 s70, s70, 2
	s_add_u32 s6, s6, 0x100
	s_addc_u32 s7, s7, 0
	s_add_u32 s68, s68, 0x100
	s_addc_u32 s69, s69, 0
	s_cmp_lt_u32 s70, 14
	s_barrier
	s_cbranch_scc1 .LBB0_1436
	v_mov_b32_e32 v134, v199
	v_mov_b32_e32 v128, v198
	s_lshl_b32 s4, s4, 8
	s_add_i32 s4, s4, s60
	v_add_u32_e32 v192, s4, v128
	v_lshlrev_b32_e32 v128, 2, v134
	v_ashrrev_i32_e32 v129, 31, v128
	v_ashrrev_i32_e32 v193, 31, v192
	v_add_u32_e32 v190, 16, v192
	v_lshl_add_u64 v[132:133], v[128:129], 2, s[8:9]
	v_lshlrev_b64 v[128:129], 6, v[192:193]
	v_ashrrev_i32_e32 v191, 31, v190
	v_add_u32_e32 v188, 32, v192
	v_lshl_add_u64 v[128:129], v[132:133], 0, v[128:129]
	v_lshlrev_b64 v[130:131], 6, v[190:191]
	v_ashrrev_i32_e32 v189, 31, v188
	v_lshl_add_u64 v[130:131], v[132:133], 0, v[130:131]
	global_load_dwordx4 v[202:205], v[128:129], off
	global_load_dwordx4 v[144:147], v[130:131], off
	v_lshlrev_b64 v[128:129], 6, v[188:189]
	v_add_u32_e32 v174, 48, v192
	v_lshl_add_u64 v[128:129], v[132:133], 0, v[128:129]
	v_ashrrev_i32_e32 v175, 31, v174
	global_load_dwordx4 v[148:151], v[128:129], off
	v_lshlrev_b64 v[128:129], 6, v[174:175]
	v_lshl_add_u64 v[128:129], v[132:133], 0, v[128:129]
	global_load_dwordx4 v[152:155], v[128:129], off
	v_add_u32_e32 v172, 0x80, v192
	v_ashrrev_i32_e32 v173, 31, v172
	v_lshlrev_b64 v[128:129], 6, v[172:173]
	v_lshl_add_u64 v[128:129], v[132:133], 0, v[128:129]
	global_load_dwordx4 v[140:143], v[128:129], off
	v_add_u32_e32 v170, 0x90, v192
	v_ashrrev_i32_e32 v171, 31, v170
	v_lshlrev_b64 v[128:129], 6, v[170:171]
	v_lshl_add_u64 v[128:129], v[132:133], 0, v[128:129]
	global_load_dwordx4 v[128:131], v[128:129], off
	s_lshl_b32 s5, s5, 7
	v_add_u32_e32 v168, 0xa0, v192
	v_add_u32_e32 v166, 0xb0, v192
	s_or_b32 s5, s5, s61
	v_ashrrev_i32_e32 v169, 31, v168
	v_ashrrev_i32_e32 v167, 31, v166
	v_lshl_add_u32 v194, v134, 3, s5
	v_lshlrev_b64 v[134:135], 6, v[168:169]
	v_lshlrev_b64 v[136:137], 6, v[166:167]
	v_lshl_add_u64 v[134:135], v[132:133], 0, v[134:135]
	v_lshl_add_u64 v[132:133], v[132:133], 0, v[136:137]
	global_load_dwordx4 v[136:139], v[134:135], off
	s_nop 0
	global_load_dwordx4 v[132:135], v[132:133], off
	s_mov_b32 s4, 0x358637bd
	v_mov_b64_e32 v[196:197], s[4:5]
	v_ashrrev_i32_e32 v195, 31, v194
	s_mov_b64 s[50:51], s[20:21]
	s_waitcnt vmcnt(0)
	v_mov_b32_e32 v206, v203
	v_mov_b32_e32 v207, v204
	v_mov_b32_e32 v203, v205
	v_mov_b32_e32 v204, v145
	v_mov_b32_e32 v205, v146
	v_mov_b32_e32 v145, v147
	v_pk_add_f32 v[202:203], v[206:207], v[202:203]
	v_mov_b32_e32 v146, v149
	v_mov_b32_e32 v147, v150
	v_mov_b32_e32 v149, v151
	v_mov_b32_e32 v150, v153
	v_mov_b32_e32 v151, v154
	v_mov_b32_e32 v153, v155
	v_pk_add_f32 v[144:145], v[204:205], v[144:145]
	v_mov_b32_e32 v155, v202
	v_pk_add_f32 v[146:147], v[146:147], v[148:149]
	v_pk_add_f32 v[148:149], v[150:151], v[152:153]
	v_mov_b32_e32 v154, v144
	v_mov_b32_e32 v202, v145
	v_mov_b32_e32 v144, v148
	v_mov_b32_e32 v145, v146
	v_mov_b32_e32 v146, v149
	v_pk_add_f32 v[148:149], v[154:155], v[202:203]
	v_pk_add_f32 v[144:145], v[144:145], v[146:147]
	v_mov_b32_e32 v147, v149
	v_mov_b32_e32 v146, v148
	v_mov_b32_e32 v151, v145
	v_mov_b32_e32 v150, v144
	v_mov_b32_e32 v152, v141
	v_mov_b32_e32 v153, v142
	v_mov_b32_e32 v141, v143
	s_waitcnt lgkmcnt(0)
	v_permlane16_swap_b32 v149, v147
	v_permlane16_swap_b32 v148, v146
	v_pk_add_f32 v[142:143], v[148:149], v[146:147]
	v_mov_b32_e32 v147, v143
	v_mov_b32_e32 v146, v142
	v_permlane16_swap_b32 v145, v151
	v_permlane16_swap_b32 v144, v150
	v_pk_add_f32 v[144:145], v[144:145], v[150:151]
	v_mov_b32_e32 v149, v145
	v_mov_b32_e32 v148, v144
	v_mov_b32_e32 v150, v129
	s_waitcnt lgkmcnt(0)
	v_permlane32_swap_b32 v143, v147
	v_permlane32_swap_b32 v142, v146
	v_pk_add_f32 v[142:143], v[142:143], v[146:147]
	v_mov_b32_e32 v151, v130
	v_pk_fma_f32 v[142:143], v[142:143], s[30:31], v[196:197] op_sel_hi:[1,0,0]
	s_waitcnt lgkmcnt(0)
	v_permlane32_swap_b32 v145, v149
	v_permlane32_swap_b32 v144, v148
	v_pk_add_f32 v[144:145], v[144:145], v[148:149]
	v_mul_f32_e32 v129, 0x4b800000, v143
	v_cmp_gt_f32_e32 vcc, s86, v143
	v_pk_fma_f32 v[146:147], v[144:145], s[30:31], v[196:197] op_sel_hi:[1,0,0]
	v_mul_f32_e32 v130, 0x4b800000, v142
	v_cndmask_b32_e32 v129, v143, v129, vcc
	v_rsq_f32_e32 v129, v129
	v_cmp_gt_f32_e64 s[4:5], s86, v142
	v_mul_f32_e32 v144, 0x4b800000, v147
	v_cmp_gt_f32_e64 s[6:7], s86, v147
	v_cndmask_b32_e64 v130, v142, v130, s[4:5]
	v_rsq_f32_e32 v142, v130
	v_cndmask_b32_e64 v130, v147, v144, s[6:7]
	v_rsq_f32_e32 v143, v130
	v_mul_f32_e32 v130, 0x45800000, v129
	v_cndmask_b32_e32 v144, v129, v130, vcc
	v_mov_b32_e32 v129, v131
	v_pk_add_f32 v[140:141], v[152:153], v[140:141]
	v_pk_add_f32 v[128:129], v[150:151], v[128:129]
	v_mov_b32_e32 v131, v140
	v_mov_b32_e32 v130, v128
	v_mov_b32_e32 v140, v129
	v_pk_add_f32 v[128:129], v[130:131], v[140:141]
	v_mov_b32_e32 v131, v129
	v_mov_b32_e32 v130, v128
	v_mul_f32_e32 v145, 0x45800000, v142
	v_cndmask_b32_e64 v142, v142, v145, s[4:5]
	v_mul_f32_e32 v140, 0x4b800000, v146
	v_cmp_gt_f32_e32 vcc, s86, v146
	s_waitcnt lgkmcnt(0)
	v_permlane16_swap_b32 v129, v131
	v_permlane16_swap_b32 v128, v130
	v_pk_add_f32 v[128:129], v[128:129], v[130:131]
	v_mov_b32_e32 v131, v129
	v_mov_b32_e32 v130, v128
	v_cndmask_b32_e32 v140, v146, v140, vcc
	v_rsq_f32_e32 v141, v140
	v_mul_f32_e32 v140, 0x45800000, v143
	v_cndmask_b32_e64 v140, v143, v140, s[6:7]
	s_waitcnt lgkmcnt(0)
	v_permlane32_swap_b32 v129, v131
	v_permlane32_swap_b32 v128, v130
	v_pk_add_f32 v[128:129], v[128:129], v[130:131]
	v_mov_b32_e32 v131, v138
	v_pk_fma_f32 v[128:129], v[128:129], s[30:31], v[196:197] op_sel_hi:[1,0,0]
	v_mul_f32_e32 v143, 0x45800000, v141
	v_mul_f32_e32 v130, 0x4b800000, v129
	v_cmp_gt_f32_e64 s[4:5], s86, v129
	v_cmp_gt_f32_e64 s[6:7], s86, v128
	v_pk_mul_f32 v[110:111], v[110:111], v[142:143] op_sel_hi:[1,0]
	v_cndmask_b32_e64 v129, v129, v130, s[4:5]
	v_mov_b32_e32 v130, v137
	v_mov_b32_e32 v137, v139
	v_pk_add_f32 v[130:131], v[130:131], v[136:137]
	v_mov_b32_e32 v136, v133
	v_mov_b32_e32 v137, v134
	v_mov_b32_e32 v133, v135
	v_pk_add_f32 v[132:133], v[136:137], v[132:133]
	v_mov_b32_e32 v135, v130
	v_mov_b32_e32 v134, v132
	v_mov_b32_e32 v130, v133
	v_pk_add_f32 v[130:131], v[134:135], v[130:131]
	v_mov_b32_e32 v133, v131
	v_mov_b32_e32 v132, v130
	v_rsq_f32_e32 v145, v129
	v_mul_f32_e32 v129, 0x4b800000, v128
	v_cndmask_b32_e64 v128, v128, v129, s[6:7]
	v_rsq_f32_e32 v135, v128
	s_waitcnt lgkmcnt(0)
	v_permlane16_swap_b32 v131, v133
	v_permlane16_swap_b32 v130, v132
	v_pk_add_f32 v[128:129], v[130:131], v[132:133]
	v_mov_b32_e32 v131, v129
	v_mov_b32_e32 v130, v128
	v_pk_mul_f32 v[126:127], v[126:127], v[144:145] op_sel_hi:[1,0]
	v_pk_mul_f32 v[122:123], v[122:123], v[144:145] op_sel_hi:[1,0]
	v_pk_mul_f32 v[116:117], v[116:117], v[144:145] op_sel_hi:[1,0]
	v_pk_mul_f32 v[124:125], v[124:125], v[144:145] op_sel_hi:[1,0]
	v_pk_mul_f32 v[138:139], v[126:127], s[44:45] op_sel_hi:[1,0]
	v_pk_mul_f32 v[120:121], v[120:121], v[144:145] op_sel_hi:[1,0]
	v_pk_mul_f32 v[122:123], v[126:127], v[122:123]
	v_pk_mul_f32 v[118:119], v[118:119], v[144:145] op_sel_hi:[1,0]
	v_pk_mul_f32 v[126:127], v[116:117], s[44:45] op_sel_hi:[1,0]
	v_pk_mul_f32 v[146:147], v[124:125], s[44:45] op_sel_hi:[1,0]
	v_pk_mul_f32 v[120:121], v[124:125], v[120:121]
	v_pk_mul_f32 v[124:125], v[118:119], s[44:45] op_sel_hi:[1,0]
	v_exp_f32_e32 v126, v126
	v_exp_f32_e32 v127, v127
	s_waitcnt lgkmcnt(0)
	v_permlane32_swap_b32 v129, v131
	v_permlane32_swap_b32 v128, v130
	v_pk_add_f32 v[128:129], v[128:129], v[130:131]
	v_exp_f32_e32 v146, v146
	v_exp_f32_e32 v138, v138
	v_exp_f32_e32 v139, v139
	v_exp_f32_e32 v147, v147
	v_exp_f32_e32 v124, v124
	v_exp_f32_e32 v125, v125
	v_pk_fma_f32 v[128:129], v[128:129], s[30:31], v[196:197] op_sel_hi:[1,0,0]
	v_cndmask_b32_e32 v136, v141, v143, vcc
	v_mul_f32_e32 v132, 0x45800000, v145
	v_mul_f32_e32 v130, 0x4b800000, v129
	v_cmp_gt_f32_e32 vcc, s86, v129
	v_cndmask_b32_e64 v134, v145, v132, s[4:5]
	v_cmp_gt_f32_e64 s[4:5], s86, v128
	v_cndmask_b32_e32 v129, v129, v130, vcc
	v_mul_f32_e32 v130, 0x4b800000, v128
	v_pk_add_f32 v[126:127], v[126:127], 1.0 op_sel_hi:[1,0]
	v_rsq_f32_e32 v129, v129
	v_cndmask_b32_e64 v128, v128, v130, s[4:5]
	v_pk_add_f32 v[138:139], v[138:139], 1.0 op_sel_hi:[1,0]
	v_pk_add_f32 v[146:147], v[146:147], 1.0 op_sel_hi:[1,0]
	v_pk_add_f32 v[124:125], v[124:125], 1.0 op_sel_hi:[1,0]
	v_rcp_f32_e32 v126, v126
	v_rcp_f32_e32 v127, v127
	v_rsq_f32_e32 v128, v128
	v_rcp_f32_e32 v146, v146
	v_rcp_f32_e32 v138, v138
	v_rcp_f32_e32 v139, v139
	v_rcp_f32_e32 v147, v147
	v_rcp_f32_e32 v124, v124
	v_rcp_f32_e32 v125, v125
	v_pk_mul_f32 v[112:113], v[112:113], v[144:145] op_sel_hi:[1,0]
	v_pk_mul_f32 v[114:115], v[114:115], v[144:145] op_sel_hi:[1,0]
	v_pk_mul_f32 v[112:113], v[116:117], v[112:113]
	v_mul_f32_e32 v130, 0x45800000, v129
	v_pk_mul_f32 v[114:115], v[118:119], v[114:115]
	v_pk_mul_f32 v[112:113], v[112:113], v[126:127]
	v_mov_b64_e32 v[126:127], 0
	v_cndmask_b32_e32 v130, v129, v130, vcc
	v_mul_f32_e32 v129, 0x45800000, v128
	v_pk_mul_f32 v[122:123], v[122:123], v[138:139]
	v_pk_mul_f32 v[120:121], v[120:121], v[146:147]
	v_pk_mul_f32 v[114:115], v[114:115], v[124:125]
	v_mov_b64_e32 v[124:125], 0
	v_cvt_pk_bf16_f32 v116, v120, v121
	v_cvt_pk_bf16_f32 v117, v122, v123
	v_mov_b64_e32 v[122:123], 0
	v_cvt_pk_bf16_f32 v118, v112, v113
	v_mov_b64_e32 v[112:113], s[10:11]
	v_cndmask_b32_e64 v128, v128, v129, s[4:5]
	v_cvt_pk_bf16_f32 v119, v114, v115
	v_mad_i64_i32 v[120:121], s[4:5], v192, s35, v[112:113]
	v_lshlrev_b64 v[114:115], 1, v[194:195]
	v_lshl_add_u64 v[120:121], v[120:121], 0, v[114:115]
	v_pk_mul_f32 v[108:109], v[108:109], v[142:143] op_sel_hi:[1,0]
	v_pk_mul_f32 v[106:107], v[106:107], v[142:143] op_sel_hi:[1,0]
	v_pk_mul_f32 v[104:105], v[104:105], v[142:143] op_sel_hi:[1,0]
	v_pk_mul_f32 v[102:103], v[102:103], v[142:143] op_sel_hi:[1,0]
	v_pk_mul_f32 v[100:101], v[100:101], v[142:143] op_sel_hi:[1,0]
	global_store_dwordx4 v[120:121], v[116:119], off
	v_pk_mul_f32 v[104:105], v[108:109], v[104:105]
	v_pk_mul_f32 v[106:107], v[110:111], v[106:107]
	v_pk_mul_f32 v[116:117], v[110:111], s[44:45] op_sel_hi:[1,0]
	v_mov_b64_e32 v[120:121], 0
	v_pk_mul_f32 v[118:119], v[108:109], s[44:45] op_sel_hi:[1,0]
	v_pk_mul_f32 v[108:109], v[102:103], s[44:45] op_sel_hi:[1,0]
	v_pk_mul_f32 v[110:111], v[100:101], s[44:45] op_sel_hi:[1,0]
	v_exp_f32_e32 v108, v108
	v_exp_f32_e32 v110, v110
	v_exp_f32_e32 v109, v109
	v_exp_f32_e32 v111, v111
	v_exp_f32_e32 v118, v118
	v_exp_f32_e32 v116, v116
	v_exp_f32_e32 v117, v117
	v_exp_f32_e32 v119, v119
	v_pk_add_f32 v[108:109], v[108:109], 1.0 op_sel_hi:[1,0]
	v_pk_add_f32 v[110:111], v[110:111], 1.0 op_sel_hi:[1,0]
	v_pk_add_f32 v[116:117], v[116:117], 1.0 op_sel_hi:[1,0]
	v_pk_add_f32 v[118:119], v[118:119], 1.0 op_sel_hi:[1,0]
	v_rcp_f32_e32 v110, v110
	v_rcp_f32_e32 v108, v108
	v_rcp_f32_e32 v109, v109
	v_rcp_f32_e32 v111, v111
	v_rcp_f32_e32 v118, v118
	v_rcp_f32_e32 v116, v116
	v_rcp_f32_e32 v117, v117
	v_rcp_f32_e32 v119, v119
	v_pk_mul_f32 v[98:99], v[98:99], v[142:143] op_sel_hi:[1,0]
	v_pk_mul_f32 v[96:97], v[96:97], v[142:143] op_sel_hi:[1,0]
	v_pk_mul_f32 v[98:99], v[102:103], v[98:99]
	v_mov_b64_e32 v[102:103], 0
	v_pk_mul_f32 v[96:97], v[100:101], v[96:97]
	v_pk_mul_f32 v[100:101], v[98:99], v[108:109]
	v_mov_b64_e32 v[108:109], 0
	v_pk_mul_f32 v[98:99], v[96:97], v[110:111]
	v_mov_b64_e32 v[110:111], 0
	v_pk_mul_f32 v[106:107], v[106:107], v[116:117]
	v_mov_b64_e32 v[116:117], 0
	v_pk_mul_f32 v[104:105], v[104:105], v[118:119]
	v_mov_b64_e32 v[118:119], 0
	v_pk_mul_f32 v[94:95], v[94:95], v[140:141] op_sel_hi:[1,0]
	v_cvt_pk_bf16_f32 v96, v104, v105
	v_mov_b64_e32 v[104:105], 0
	v_cvt_pk_bf16_f32 v97, v106, v107
	v_mov_b64_e32 v[106:107], 0
	v_cvt_pk_bf16_f32 v98, v98, v99
	v_cvt_pk_bf16_f32 v99, v100, v101
	v_mad_i64_i32 v[100:101], s[4:5], v190, s35, v[112:113]
	v_lshl_add_u64 v[100:101], v[100:101], 0, v[114:115]
	v_pk_mul_f32 v[92:93], v[92:93], v[140:141] op_sel_hi:[1,0]
	v_pk_mul_f32 v[90:91], v[90:91], v[140:141] op_sel_hi:[1,0]
	v_pk_mul_f32 v[88:89], v[88:89], v[140:141] op_sel_hi:[1,0]
	v_pk_mul_f32 v[86:87], v[86:87], v[140:141] op_sel_hi:[1,0]
	v_pk_mul_f32 v[84:85], v[84:85], v[140:141] op_sel_hi:[1,0]
	global_store_dwordx4 v[100:101], v[96:99], off
	v_pk_mul_f32 v[88:89], v[92:93], v[88:89]
	v_pk_mul_f32 v[90:91], v[94:95], v[90:91]
	v_pk_mul_f32 v[96:97], v[94:95], s[44:45] op_sel_hi:[1,0]
	v_mov_b64_e32 v[100:101], 0
	v_pk_mul_f32 v[98:99], v[92:93], s[44:45] op_sel_hi:[1,0]
	v_pk_mul_f32 v[92:93], v[86:87], s[44:45] op_sel_hi:[1,0]
	v_pk_mul_f32 v[94:95], v[84:85], s[44:45] op_sel_hi:[1,0]
	v_exp_f32_e32 v92, v92
	v_exp_f32_e32 v94, v94
	v_exp_f32_e32 v93, v93
	v_exp_f32_e32 v95, v95
	v_exp_f32_e32 v98, v98
	v_exp_f32_e32 v96, v96
	v_exp_f32_e32 v97, v97
	v_exp_f32_e32 v99, v99
	v_pk_add_f32 v[92:93], v[92:93], 1.0 op_sel_hi:[1,0]
	v_pk_add_f32 v[94:95], v[94:95], 1.0 op_sel_hi:[1,0]
	v_pk_add_f32 v[96:97], v[96:97], 1.0 op_sel_hi:[1,0]
	v_pk_add_f32 v[98:99], v[98:99], 1.0 op_sel_hi:[1,0]
	v_rcp_f32_e32 v94, v94
	v_rcp_f32_e32 v92, v92
	v_rcp_f32_e32 v93, v93
	v_rcp_f32_e32 v95, v95
	v_rcp_f32_e32 v98, v98
	v_rcp_f32_e32 v96, v96
	v_rcp_f32_e32 v97, v97
	v_rcp_f32_e32 v99, v99
	v_pk_mul_f32 v[82:83], v[82:83], v[140:141] op_sel_hi:[1,0]
	v_pk_mul_f32 v[80:81], v[80:81], v[140:141] op_sel_hi:[1,0]
	v_pk_mul_f32 v[82:83], v[86:87], v[82:83]
	v_mov_b64_e32 v[86:87], 0
	v_pk_mul_f32 v[80:81], v[84:85], v[80:81]
	v_pk_mul_f32 v[84:85], v[82:83], v[92:93]
	v_mov_b64_e32 v[92:93], 0
	v_pk_mul_f32 v[82:83], v[80:81], v[94:95]
	v_mov_b64_e32 v[94:95], 0
	v_pk_mul_f32 v[90:91], v[90:91], v[96:97]
	v_mov_b64_e32 v[96:97], 0
	v_pk_mul_f32 v[88:89], v[88:89], v[98:99]
	v_mov_b64_e32 v[98:99], 0
	v_pk_mul_f32 v[78:79], v[78:79], v[136:137] op_sel_hi:[1,0]
	v_cvt_pk_bf16_f32 v80, v88, v89
	v_mov_b64_e32 v[88:89], 0
	v_cvt_pk_bf16_f32 v81, v90, v91
	v_mov_b64_e32 v[90:91], 0
	v_cvt_pk_bf16_f32 v82, v82, v83
	v_cvt_pk_bf16_f32 v83, v84, v85
	v_mad_i64_i32 v[84:85], s[4:5], v188, s35, v[112:113]
	v_lshl_add_u64 v[84:85], v[84:85], 0, v[114:115]
	v_pk_mul_f32 v[76:77], v[76:77], v[136:137] op_sel_hi:[1,0]
	v_pk_mul_f32 v[74:75], v[74:75], v[136:137] op_sel_hi:[1,0]
	v_pk_mul_f32 v[72:73], v[72:73], v[136:137] op_sel_hi:[1,0]
	v_pk_mul_f32 v[70:71], v[70:71], v[136:137] op_sel_hi:[1,0]
	v_pk_mul_f32 v[68:69], v[68:69], v[136:137] op_sel_hi:[1,0]
	global_store_dwordx4 v[84:85], v[80:83], off
	v_pk_mul_f32 v[72:73], v[76:77], v[72:73]
	v_pk_mul_f32 v[74:75], v[78:79], v[74:75]
	v_pk_mul_f32 v[80:81], v[78:79], s[44:45] op_sel_hi:[1,0]
	v_mov_b64_e32 v[84:85], 0
	v_pk_mul_f32 v[82:83], v[76:77], s[44:45] op_sel_hi:[1,0]
	v_pk_mul_f32 v[76:77], v[70:71], s[44:45] op_sel_hi:[1,0]
	v_pk_mul_f32 v[78:79], v[68:69], s[44:45] op_sel_hi:[1,0]
	v_exp_f32_e32 v76, v76
	v_exp_f32_e32 v78, v78
	v_exp_f32_e32 v77, v77
	v_exp_f32_e32 v79, v79
	v_exp_f32_e32 v82, v82
	v_exp_f32_e32 v80, v80
	v_exp_f32_e32 v81, v81
	v_exp_f32_e32 v83, v83
	v_pk_add_f32 v[76:77], v[76:77], 1.0 op_sel_hi:[1,0]
	v_pk_add_f32 v[78:79], v[78:79], 1.0 op_sel_hi:[1,0]
	v_pk_add_f32 v[80:81], v[80:81], 1.0 op_sel_hi:[1,0]
	v_pk_add_f32 v[82:83], v[82:83], 1.0 op_sel_hi:[1,0]
	v_rcp_f32_e32 v78, v78
	v_rcp_f32_e32 v76, v76
	v_rcp_f32_e32 v77, v77
	v_rcp_f32_e32 v79, v79
	v_rcp_f32_e32 v82, v82
	v_rcp_f32_e32 v80, v80
	v_rcp_f32_e32 v81, v81
	v_rcp_f32_e32 v83, v83
	v_pk_mul_f32 v[66:67], v[66:67], v[136:137] op_sel_hi:[1,0]
	v_pk_mul_f32 v[64:65], v[64:65], v[136:137] op_sel_hi:[1,0]
	v_pk_mul_f32 v[66:67], v[70:71], v[66:67]
	v_mov_b64_e32 v[70:71], 0
	v_pk_mul_f32 v[64:65], v[68:69], v[64:65]
	v_pk_mul_f32 v[68:69], v[66:67], v[76:77]
	v_mov_b64_e32 v[76:77], 0
	v_pk_mul_f32 v[66:67], v[64:65], v[78:79]
	v_mov_b64_e32 v[78:79], 0
	v_pk_mul_f32 v[74:75], v[74:75], v[80:81]
	v_mov_b64_e32 v[80:81], 0
	v_pk_mul_f32 v[72:73], v[72:73], v[82:83]
	v_mov_b64_e32 v[82:83], 0
	v_pk_mul_f32 v[62:63], v[62:63], v[134:135] op_sel_hi:[1,0]
	v_cvt_pk_bf16_f32 v64, v72, v73
	v_mov_b64_e32 v[72:73], 0
	v_cvt_pk_bf16_f32 v65, v74, v75
	v_mov_b64_e32 v[74:75], 0
	v_cvt_pk_bf16_f32 v66, v66, v67
	v_cvt_pk_bf16_f32 v67, v68, v69
	v_mad_i64_i32 v[68:69], s[4:5], v174, s35, v[112:113]
	v_lshl_add_u64 v[68:69], v[68:69], 0, v[114:115]
	v_pk_mul_f32 v[60:61], v[60:61], v[134:135] op_sel_hi:[1,0]
	v_pk_mul_f32 v[58:59], v[58:59], v[134:135] op_sel_hi:[1,0]
	v_pk_mul_f32 v[56:57], v[56:57], v[134:135] op_sel_hi:[1,0]
	v_pk_mul_f32 v[54:55], v[54:55], v[134:135] op_sel_hi:[1,0]
	v_pk_mul_f32 v[52:53], v[52:53], v[134:135] op_sel_hi:[1,0]
	global_store_dwordx4 v[68:69], v[64:67], off
	v_pk_mul_f32 v[56:57], v[60:61], v[56:57]
	v_pk_mul_f32 v[58:59], v[62:63], v[58:59]
	v_pk_mul_f32 v[64:65], v[62:63], s[44:45] op_sel_hi:[1,0]
	v_mov_b64_e32 v[68:69], 0
	v_pk_mul_f32 v[66:67], v[60:61], s[44:45] op_sel_hi:[1,0]
	v_pk_mul_f32 v[60:61], v[54:55], s[44:45] op_sel_hi:[1,0]
	v_pk_mul_f32 v[62:63], v[52:53], s[44:45] op_sel_hi:[1,0]
	v_exp_f32_e32 v60, v60
	v_exp_f32_e32 v62, v62
	v_exp_f32_e32 v61, v61
	v_exp_f32_e32 v63, v63
	v_exp_f32_e32 v66, v66
	v_exp_f32_e32 v64, v64
	v_exp_f32_e32 v65, v65
	v_exp_f32_e32 v67, v67
	v_pk_add_f32 v[60:61], v[60:61], 1.0 op_sel_hi:[1,0]
	v_pk_add_f32 v[62:63], v[62:63], 1.0 op_sel_hi:[1,0]
	v_pk_add_f32 v[64:65], v[64:65], 1.0 op_sel_hi:[1,0]
	v_pk_add_f32 v[66:67], v[66:67], 1.0 op_sel_hi:[1,0]
	v_rcp_f32_e32 v62, v62
	v_rcp_f32_e32 v60, v60
	v_rcp_f32_e32 v61, v61
	v_rcp_f32_e32 v63, v63
	v_rcp_f32_e32 v66, v66
	v_rcp_f32_e32 v64, v64
	v_rcp_f32_e32 v65, v65
	v_rcp_f32_e32 v67, v67
	v_pk_mul_f32 v[50:51], v[50:51], v[134:135] op_sel_hi:[1,0]
	v_pk_mul_f32 v[48:49], v[48:49], v[134:135] op_sel_hi:[1,0]
	v_pk_mul_f32 v[50:51], v[54:55], v[50:51]
	v_mov_b64_e32 v[54:55], 0
	v_pk_mul_f32 v[48:49], v[52:53], v[48:49]
	v_mul_f32_e32 v132, 0x45800000, v135
	v_pk_mul_f32 v[52:53], v[50:51], v[60:61]
	v_mov_b64_e32 v[60:61], 0
	v_pk_mul_f32 v[50:51], v[48:49], v[62:63]
	v_mov_b64_e32 v[62:63], 0
	v_cndmask_b32_e64 v132, v135, v132, s[6:7]
	v_pk_mul_f32 v[58:59], v[58:59], v[64:65]
	v_mov_b64_e32 v[64:65], 0
	v_pk_mul_f32 v[56:57], v[56:57], v[66:67]
	v_mov_b64_e32 v[66:67], 0
	v_pk_mul_f32 v[46:47], v[46:47], v[132:133] op_sel_hi:[1,0]
	v_cvt_pk_bf16_f32 v48, v56, v57
	v_mov_b64_e32 v[56:57], 0
	v_cvt_pk_bf16_f32 v49, v58, v59
	v_mov_b64_e32 v[58:59], 0
	v_cvt_pk_bf16_f32 v50, v50, v51
	v_cvt_pk_bf16_f32 v51, v52, v53
	v_mad_i64_i32 v[52:53], s[4:5], v172, s35, v[112:113]
	v_lshl_add_u64 v[52:53], v[52:53], 0, v[114:115]
	v_pk_mul_f32 v[44:45], v[44:45], v[132:133] op_sel_hi:[1,0]
	v_pk_mul_f32 v[42:43], v[42:43], v[132:133] op_sel_hi:[1,0]
	v_pk_mul_f32 v[40:41], v[40:41], v[132:133] op_sel_hi:[1,0]
	v_pk_mul_f32 v[38:39], v[38:39], v[132:133] op_sel_hi:[1,0]
	v_pk_mul_f32 v[36:37], v[36:37], v[132:133] op_sel_hi:[1,0]
	global_store_dwordx4 v[52:53], v[48:51], off
	v_pk_mul_f32 v[40:41], v[44:45], v[40:41]
	v_pk_mul_f32 v[42:43], v[46:47], v[42:43]
	v_pk_mul_f32 v[48:49], v[46:47], s[44:45] op_sel_hi:[1,0]
	v_mov_b64_e32 v[52:53], 0
	v_pk_mul_f32 v[50:51], v[44:45], s[44:45] op_sel_hi:[1,0]
	v_pk_mul_f32 v[44:45], v[38:39], s[44:45] op_sel_hi:[1,0]
	v_pk_mul_f32 v[46:47], v[36:37], s[44:45] op_sel_hi:[1,0]
	v_exp_f32_e32 v44, v44
	v_exp_f32_e32 v46, v46
	v_exp_f32_e32 v45, v45
	v_exp_f32_e32 v47, v47
	v_exp_f32_e32 v50, v50
	v_exp_f32_e32 v48, v48
	v_exp_f32_e32 v49, v49
	v_exp_f32_e32 v51, v51
	v_pk_add_f32 v[44:45], v[44:45], 1.0 op_sel_hi:[1,0]
	v_pk_add_f32 v[46:47], v[46:47], 1.0 op_sel_hi:[1,0]
	v_pk_add_f32 v[48:49], v[48:49], 1.0 op_sel_hi:[1,0]
	v_pk_add_f32 v[50:51], v[50:51], 1.0 op_sel_hi:[1,0]
	v_rcp_f32_e32 v46, v46
	v_rcp_f32_e32 v44, v44
	v_rcp_f32_e32 v45, v45
	v_rcp_f32_e32 v47, v47
	v_rcp_f32_e32 v50, v50
	v_rcp_f32_e32 v48, v48
	v_rcp_f32_e32 v49, v49
	v_rcp_f32_e32 v51, v51
	v_pk_mul_f32 v[34:35], v[34:35], v[132:133] op_sel_hi:[1,0]
	v_pk_mul_f32 v[32:33], v[32:33], v[132:133] op_sel_hi:[1,0]
	v_pk_mul_f32 v[34:35], v[38:39], v[34:35]
	v_mov_b64_e32 v[38:39], 0
	v_pk_mul_f32 v[32:33], v[36:37], v[32:33]
	v_pk_mul_f32 v[36:37], v[34:35], v[44:45]
	v_mov_b64_e32 v[44:45], 0
	v_pk_mul_f32 v[34:35], v[32:33], v[46:47]
	v_mov_b64_e32 v[46:47], 0
	v_pk_mul_f32 v[42:43], v[42:43], v[48:49]
	v_mov_b64_e32 v[48:49], 0
	v_pk_mul_f32 v[40:41], v[40:41], v[50:51]
	v_mov_b64_e32 v[50:51], 0
	v_pk_mul_f32 v[30:31], v[30:31], v[130:131] op_sel_hi:[1,0]
	v_cvt_pk_bf16_f32 v32, v40, v41
	v_mov_b64_e32 v[40:41], 0
	v_cvt_pk_bf16_f32 v33, v42, v43
	v_mov_b64_e32 v[42:43], 0
	v_cvt_pk_bf16_f32 v34, v34, v35
	v_cvt_pk_bf16_f32 v35, v36, v37
	v_mad_i64_i32 v[36:37], s[4:5], v170, s35, v[112:113]
	v_lshl_add_u64 v[36:37], v[36:37], 0, v[114:115]
	v_pk_mul_f32 v[28:29], v[28:29], v[130:131] op_sel_hi:[1,0]
	v_pk_mul_f32 v[26:27], v[26:27], v[130:131] op_sel_hi:[1,0]
	v_pk_mul_f32 v[24:25], v[24:25], v[130:131] op_sel_hi:[1,0]
	v_pk_mul_f32 v[22:23], v[22:23], v[130:131] op_sel_hi:[1,0]
	v_pk_mul_f32 v[20:21], v[20:21], v[130:131] op_sel_hi:[1,0]
	global_store_dwordx4 v[36:37], v[32:35], off
	v_pk_mul_f32 v[24:25], v[28:29], v[24:25]
	v_pk_mul_f32 v[26:27], v[30:31], v[26:27]
	v_pk_mul_f32 v[32:33], v[30:31], s[44:45] op_sel_hi:[1,0]
	v_mov_b64_e32 v[36:37], 0
	v_pk_mul_f32 v[34:35], v[28:29], s[44:45] op_sel_hi:[1,0]
	v_pk_mul_f32 v[28:29], v[22:23], s[44:45] op_sel_hi:[1,0]
	v_pk_mul_f32 v[30:31], v[20:21], s[44:45] op_sel_hi:[1,0]
	v_exp_f32_e32 v28, v28
	v_exp_f32_e32 v30, v30
	v_exp_f32_e32 v29, v29
	v_exp_f32_e32 v31, v31
	v_exp_f32_e32 v34, v34
	v_exp_f32_e32 v32, v32
	v_exp_f32_e32 v33, v33
	v_exp_f32_e32 v35, v35
	v_pk_add_f32 v[28:29], v[28:29], 1.0 op_sel_hi:[1,0]
	v_pk_add_f32 v[30:31], v[30:31], 1.0 op_sel_hi:[1,0]
	v_pk_add_f32 v[32:33], v[32:33], 1.0 op_sel_hi:[1,0]
	v_pk_add_f32 v[34:35], v[34:35], 1.0 op_sel_hi:[1,0]
	v_rcp_f32_e32 v30, v30
	v_rcp_f32_e32 v28, v28
	v_rcp_f32_e32 v29, v29
	v_rcp_f32_e32 v31, v31
	v_rcp_f32_e32 v34, v34
	v_rcp_f32_e32 v32, v32
	v_rcp_f32_e32 v33, v33
	v_rcp_f32_e32 v35, v35
	v_pk_mul_f32 v[18:19], v[18:19], v[130:131] op_sel_hi:[1,0]
	v_pk_mul_f32 v[16:17], v[16:17], v[130:131] op_sel_hi:[1,0]
	v_pk_mul_f32 v[18:19], v[22:23], v[18:19]
	v_mov_b64_e32 v[22:23], 0
	v_pk_mul_f32 v[16:17], v[20:21], v[16:17]
	v_pk_mul_f32 v[20:21], v[18:19], v[28:29]
	v_mov_b64_e32 v[28:29], 0
	v_pk_mul_f32 v[18:19], v[16:17], v[30:31]
	v_mov_b64_e32 v[30:31], 0
	v_pk_mul_f32 v[26:27], v[26:27], v[32:33]
	v_mov_b64_e32 v[32:33], 0
	v_pk_mul_f32 v[24:25], v[24:25], v[34:35]
	v_mov_b64_e32 v[34:35], 0
	v_pk_mul_f32 v[14:15], v[14:15], v[128:129] op_sel_hi:[1,0]
	v_cvt_pk_bf16_f32 v16, v24, v25
	v_mov_b64_e32 v[24:25], 0
	v_cvt_pk_bf16_f32 v17, v26, v27
	v_mov_b64_e32 v[26:27], 0
	v_cvt_pk_bf16_f32 v18, v18, v19
	v_cvt_pk_bf16_f32 v19, v20, v21
	v_mad_i64_i32 v[20:21], s[4:5], v168, s35, v[112:113]
	v_lshl_add_u64 v[20:21], v[20:21], 0, v[114:115]
	v_pk_mul_f32 v[12:13], v[12:13], v[128:129] op_sel_hi:[1,0]
	v_pk_mul_f32 v[10:11], v[10:11], v[128:129] op_sel_hi:[1,0]
	v_pk_mul_f32 v[8:9], v[8:9], v[128:129] op_sel_hi:[1,0]
	v_pk_mul_f32 v[6:7], v[6:7], v[128:129] op_sel_hi:[1,0]
	v_pk_mul_f32 v[4:5], v[4:5], v[128:129] op_sel_hi:[1,0]
	global_store_dwordx4 v[20:21], v[16:19], off
	v_pk_mul_f32 v[8:9], v[12:13], v[8:9]
	v_pk_mul_f32 v[10:11], v[14:15], v[10:11]
	v_pk_mul_f32 v[16:17], v[14:15], s[44:45] op_sel_hi:[1,0]
	v_mov_b64_e32 v[20:21], 0
	v_pk_mul_f32 v[18:19], v[12:13], s[44:45] op_sel_hi:[1,0]
	v_pk_mul_f32 v[12:13], v[6:7], s[44:45] op_sel_hi:[1,0]
	v_pk_mul_f32 v[14:15], v[4:5], s[44:45] op_sel_hi:[1,0]
	v_exp_f32_e32 v12, v12
	v_exp_f32_e32 v14, v14
	v_exp_f32_e32 v13, v13
	v_exp_f32_e32 v15, v15
	v_exp_f32_e32 v18, v18
	v_exp_f32_e32 v16, v16
	v_exp_f32_e32 v17, v17
	v_exp_f32_e32 v19, v19
	v_pk_add_f32 v[12:13], v[12:13], 1.0 op_sel_hi:[1,0]
	v_pk_add_f32 v[14:15], v[14:15], 1.0 op_sel_hi:[1,0]
	v_pk_add_f32 v[16:17], v[16:17], 1.0 op_sel_hi:[1,0]
	v_pk_add_f32 v[18:19], v[18:19], 1.0 op_sel_hi:[1,0]
	v_rcp_f32_e32 v14, v14
	v_rcp_f32_e32 v12, v12
	v_rcp_f32_e32 v13, v13
	v_rcp_f32_e32 v15, v15
	v_rcp_f32_e32 v18, v18
	v_rcp_f32_e32 v16, v16
	v_rcp_f32_e32 v17, v17
	v_rcp_f32_e32 v19, v19
	v_pk_mul_f32 v[2:3], v[2:3], v[128:129] op_sel_hi:[1,0]
	v_pk_mul_f32 v[0:1], v[0:1], v[128:129] op_sel_hi:[1,0]
	v_pk_mul_f32 v[2:3], v[6:7], v[2:3]
	v_mov_b64_e32 v[6:7], 0
	v_pk_mul_f32 v[0:1], v[4:5], v[0:1]
	v_pk_mul_f32 v[4:5], v[2:3], v[12:13]
	v_mov_b64_e32 v[12:13], 0
	v_pk_mul_f32 v[2:3], v[0:1], v[14:15]
	v_mov_b64_e32 v[14:15], 0
	v_pk_mul_f32 v[10:11], v[10:11], v[16:17]
	v_mov_b64_e32 v[16:17], 0
	v_pk_mul_f32 v[8:9], v[8:9], v[18:19]
	v_mov_b64_e32 v[18:19], 0
	s_andn2_b64 vcc, exec, s[2:3]
	v_cvt_pk_bf16_f32 v0, v8, v9
	v_mov_b64_e32 v[8:9], 0
	v_cvt_pk_bf16_f32 v1, v10, v11
	v_mov_b64_e32 v[10:11], 0
	v_cvt_pk_bf16_f32 v2, v2, v3
	v_cvt_pk_bf16_f32 v3, v4, v5
	v_mad_i64_i32 v[4:5], s[4:5], v166, s35, v[112:113]
	v_mov_b64_e32 v[112:113], 0
	v_lshl_add_u64 v[4:5], v[4:5], 0, v[114:115]
	v_mov_b64_e32 v[114:115], 0
	s_mov_b32 s4, s16
	s_mov_b32 s5, s12
	s_mov_b64 s[6:7], s[18:19]
	global_store_dwordx4 v[4:5], v[0:3], off
	s_cbranch_vccnz .LBB0_1429
	s_waitcnt vmcnt(0)
	s_cmpk_gt_u32 s24, 0xff
	s_cbranch_scc1 .LBB0_1440
	s_barrier
